# grid barrier release side made flat: non-leader workgroups poll the top-level generation word (TOPGEN) directly instead of their XCD's XGEN word (one dependent hop less per barrier), on top of v25
# baseline (speedup 1.0000x reference)
.LBB0_80:
	s_or_b64 exec, exec, s[6:7]
	s_waitcnt lgkmcnt(1)
	v_cvt_f32_u32_e32 v5, v3
	s_waitcnt vmcnt(0)
	v_readfirstlane_b32 s4, v4
	v_sub_u32_e32 v4, 0, v3
	v_rcp_iflag_f32_e32 v5, v5
	v_add_u32_e32 v6, s4, v2
	v_mul_f32_e32 v5, 0x4f7ffffe, v5
	v_cvt_u32_f32_e32 v5, v5
	v_mul_lo_u32 v2, v4, v5
	v_mul_hi_u32 v2, v5, v2
	v_add_u32_e32 v2, v5, v2
	v_mul_hi_u32 v2, v6, v2
	v_mul_lo_u32 v4, v2, v3
	v_sub_u32_e32 v4, v6, v4
	v_add_u32_e32 v5, 1, v2
	v_cmp_ge_u32_e32 vcc, v4, v3
	s_nop 1
	v_cndmask_b32_e32 v2, v2, v5, vcc
	v_sub_u32_e32 v5, v4, v3
	v_cndmask_b32_e32 v4, v4, v5, vcc
	v_add_u32_e32 v5, 1, v2
	v_cmp_ge_u32_e32 vcc, v4, v3
	v_add_u32_e32 v4, 1, v6
	s_nop 0
	v_cndmask_b32_e32 v2, v2, v5, vcc
	v_mul_lo_u32 v5, v3, v2
	v_add_u32_e32 v3, v5, v3
	v_cmp_ne_u32_e32 vcc, v4, v3
	s_and_saveexec_b64 s[4:5], vcc
	s_xor_b64 s[4:5], exec, s[4:5]
	s_cbranch_execz .LBB0_94
	s_waitcnt lgkmcnt(0)
	v_mov_b32_e32 v1, 0
	v_readlane_b32 s10, v253, 31
	v_readlane_b32 s11, v253, 32
	s_nop 3
	s_add_u32 s10, s10, 0x3500
	s_addc_u32 s11, s11, 0
	global_load_dword v1, v1, s[10:11] sc1
	s_waitcnt vmcnt(0)
	v_cmp_eq_u32_e32 vcc, v1, v2
	s_and_saveexec_b64 s[6:7], vcc
	s_cbranch_execz .LBB0_93
	s_add_u32 s8, s84, 0x4200
	s_addc_u32 s9, s85, 0
	s_mov_b32 s22, 1
	s_mov_b64 s[12:13], 0
	v_mov_b32_e32 v1, 0
	s_branch .LBB0_84

.LBB0_384:
	s_or_b64 exec, exec, s[10:11]
	s_waitcnt lgkmcnt(1)
	v_cvt_f32_u32_e32 v6, v3
	s_waitcnt vmcnt(0)
	v_readfirstlane_b32 s2, v5
	v_sub_u32_e32 v5, 0, v3
	v_rcp_iflag_f32_e32 v6, v6
	v_add_u32_e32 v7, s2, v1
	v_mul_f32_e32 v6, 0x4f7ffffe, v6
	v_cvt_u32_f32_e32 v6, v6
	v_mul_lo_u32 v1, v5, v6
	v_mul_hi_u32 v1, v6, v1
	v_add_u32_e32 v1, v6, v1
	v_mul_hi_u32 v1, v7, v1
	v_mul_lo_u32 v5, v1, v3
	v_sub_u32_e32 v5, v7, v5
	v_add_u32_e32 v6, 1, v1
	v_cmp_ge_u32_e32 vcc, v5, v3
	s_nop 1
	v_cndmask_b32_e32 v1, v1, v6, vcc
	v_sub_u32_e32 v6, v5, v3
	v_cndmask_b32_e32 v5, v5, v6, vcc
	v_add_u32_e32 v6, 1, v1
	v_cmp_ge_u32_e32 vcc, v5, v3
	v_add_u32_e32 v5, 1, v7
	s_nop 0
	v_cndmask_b32_e32 v1, v1, v6, vcc
	v_mul_lo_u32 v6, v3, v1
	v_add_u32_e32 v3, v6, v3
	v_cmp_ne_u32_e32 vcc, v5, v3
	s_and_saveexec_b64 s[2:3], vcc
	s_xor_b64 s[8:9], exec, s[2:3]
	s_cbranch_execz .LBB0_398
	s_waitcnt lgkmcnt(0)
	v_mov_b32_e32 v2, 0
	v_readlane_b32 s12, v253, 31
	v_readlane_b32 s13, v253, 32
	s_nop 3
	s_add_u32 s12, s12, 0x3500
	s_addc_u32 s13, s13, 0
	global_load_dword v2, v2, s[12:13] sc1
	s_waitcnt vmcnt(0)
	v_cmp_eq_u32_e32 vcc, v2, v1
	s_and_saveexec_b64 s[10:11], vcc
	s_cbranch_execz .LBB0_397
	s_mov_b32 s2, 1
	s_mov_b64 s[14:15], 0
	s_branch .LBB0_388
